# grid barrier: two-level arrival (4 group counters by blockIdx&3, last arriver bumps top counter) instead of 256 atomics on one word
# speedup vs baseline: 1.0295x; 1.0295x over previous
; DI void fast_grid_barrier(unsigned* ctr, unsigned target) {
;     asm volatile("s_waitcnt vmcnt(0)" ::: "memory");
;     __syncthreads();
;     if (threadIdx.x == 0) {
;         __builtin_amdgcn_fence(__ATOMIC_RELEASE, "agent");
;         asm volatile("s_waitcnt vmcnt(0)" ::: "memory");
;         __hip_atomic_fetch_add(ctr, 1u, __ATOMIC_RELAXED, __HIP_MEMORY_SCOPE_AGENT);
;         while (__hip_atomic_load(ctr, __ATOMIC_RELAXED, __HIP_MEMORY_SCOPE_AGENT) < target) __builtin_amdgcn_s_sleep(1);
;         __builtin_amdgcn_fence(__ATOMIC_ACQUIRE, "agent");
;         asm volatile("s_waitcnt vmcnt(0)" ::: "memory");
;     }
;     __syncthreads();
; }
.LBB0_4:
	s_cmp_le_i32 s70, s12
	s_cbranch_scc1 .LBB0_26
	v_readlane_b32 s0, v255, 4
	s_cmp_lg_u32 s70, s0
	s_mov_b64 s[0:1], -1
	s_waitcnt vmcnt(0)
	v_readlane_b32 s0, v255, 11
	s_add_i32 s4, s0, 1
	s_barrier
	s_mov_b64 s[0:1], exec
	v_readlane_b32 s6, v255, 12
	v_readlane_b32 s7, v255, 13
	s_and_b64 s[6:7], s[0:1], s[6:7]
	s_mov_b64 exec, s[6:7]
	s_cbranch_execz .LBB0_12
	buffer_wbl2 sc1
	s_waitcnt vmcnt(0)
	s_and_b32 s5, s2, 3
	s_lshl_b32 s8, s5, 6
	s_cmp_eq_u32 s5, 0
	s_cselect_b32 s8, 32, s8
	v_mov_b32_e32 v0, 1
	v_mov_b32_e32 v1, s8
	global_atomic_add v2, v1, v0, s[14:15] sc0
	s_sub_i32 s9, s72, s5
	s_add_i32 s9, s9, 3
	s_lshr_b32 s9, s9, 2
	s_mul_i32 s9, s9, s4
	s_lshl_b32 s5, s4, 2
	s_waitcnt vmcnt(0)
	v_add_u32_e32 v2, 1, v2
	v_cmp_eq_u32_e32 vcc, s9, v2
	s_cbranch_vccz .Lgb_poll
	global_atomic_add v165, v0, s[14:15]
.Lgb_poll:
	global_load_dword v0, v165, s[14:15] sc1
	s_waitcnt vmcnt(0)
	v_cmp_le_u32_e32 vcc, s5, v0
	s_cbranch_vccnz .LBB0_11
